# v32 with the P2/P3 first/last split keyed on permuted-id bit 4 (blocks of 16 units / 4 heads alternate)
# baseline (speedup 1.0000x reference)
; #define LAS __attribute__((address_space(3)))
; DI float bf2f(unsigned short u) { return __uint_as_float(((unsigned)u) << 16); }
; DI float gamma_of(int h) { return 1.0f - exp2f(-5.0f - (float)h); }
; DI void ret_decode_unit(LAS unsigned char* lds, const bf16_t* Z, const float* S0, float* S1, bf16_t* MIX, const float* rng, int b, int h, int tid) {
;     LAS float* qv = (LAS float*)lds; LAS float* red = qv + 768;
;     const int lane = tid & 63, wid = tid >> 6;
;     const bf16_t* zrow = Z + (size_t)(LP + b) * INW;
;     if (tid < 256) { qv[tid] = bf2f(zrow[C_RQ + h * 256 + tid]); qv[256 + tid] = bf2f(zrow[C_RK + h * 256 + tid]); qv[512 + tid] = bf2f(zrow[C_RV + h * 256 + tid]); }
;     __syncthreads();
;     const float gm = gamma_of(h);
;     const f32x4 v4 = *(const LAS f32x4*)(qv + 512 + 4 * lane);
;     f32x4 acc = {0.f, 0.f, 0.f, 0.f};
;     const size_t off = ((size_t)(b * 4 + h) * 256 + wid * 32) * 256 + 4 * lane;
;     const float* s0 = S0 + off; float* s1 = S1 + off;
; __global__ void __launch_bounds__(512, 2) fwd_kernel(Args a) {
;     ...
;     if (IN(2)) for (int rep_ = 0; rep_ < 1 + ((DUPMASK >> 2) & 1); ++rep_) { if (rep_) xcd_barrier(bar);
;         if (bx & 1) for (int u = bx; u < 256; u += G) ret_decode_unit(lds, Z, state0, out + O_SS, MIX, rng, u >> 2, u & 3, tid);
;         for (int u = bx; u < 256; u += G) ret_step1(lds, Z, KV, u >> 2, u & 3, tid);
;         if (!(bx & 1)) for (int u = bx; u < 256; u += G) ret_decode_unit(lds, Z, state0, out + O_SS, MIX, rng, u >> 2, u & 3, tid);
;     }
.LBB0_226:
	s_and_b32 s98, s92, 7
	s_lshl_b32 s98, s98, 5
	s_lshr_b32 s99, s92, 3
	s_or_b32 s92, s98, s99
	s_cmp_lt_i32 s62, 3
	s_cselect_b64 s[2:3], -1, 0
	s_add_u32 s56, s60, 0x8000000
	s_addc_u32 s57, s61, 0
	s_add_u32 s4, s60, 0xfc00000
	s_addc_u32 s5, s61, 0
	v_writelane_b32 v254, s4, 23
	s_and_b64 s[10:11], s[2:3], s[0:1]
	s_andn2_b64 vcc, exec, s[10:11]
	v_writelane_b32 v254, s5, 24
	v_lshrrev_b32_e32 v252, 6, v253
	v_cmp_gt_u32_e64 s[0:1], 64, v253
	s_cbranch_vccnz .LBB0_250
	s_bitcmp0_b32 s92, 4
	v_readlane_b32 s68, v254, 7
	s_cselect_b64 s[14:15], -1, 0
	s_cmpk_gt_i32 s92, 0xff
	v_readlane_b32 s82, v254, 21
	v_lshlrev_b32_e32 v0, 2, v253
	s_cselect_b64 s[2:3], -1, 0
	v_readlane_b32 s83, v254, 22
	s_add_u32 s12, s82, 0x5220000
	v_and_b32_e32 v147, 0xfc, v0
	v_readlane_b32 s72, v254, 11
	v_readlane_b32 s73, v254, 12
	s_addc_u32 s13, s83, 0
	s_movk_i32 s4, 0x100
	v_add_u32_e32 v146, 0, v0
	v_lshlrev_b32_e32 v20, 2, v147
	v_mov_b32_e32 v21, 0
	v_lshl_add_u32 v149, v252, 7, 0
	v_mul_u32_u24_e32 v0, 0x380, v252
	s_or_b64 s[2:3], s[14:15], s[2:3]
	s_mov_b32 s17, 0
	v_add_u32_e32 v144, 0x900, v253
	v_add_u32_e32 v145, 0xd00, v253
	v_cmp_gt_u32_e64 s[6:7], s4, v253
	v_add_u32_e32 v148, 0, v20
	v_lshl_or_b32 v128, v252, 13, v147
	v_mov_b32_e32 v129, v21
	v_add3_u32 v150, v149, v0, v20
	v_lshl_add_u64 v[130:131], s[72:73], 0, v[20:21]
	s_and_b64 vcc, exec, s[2:3]
	v_readlane_b32 s69, v254, 8
	v_readlane_b32 s70, v254, 9
	v_readlane_b32 s71, v254, 10
	v_readlane_b32 s74, v254, 13
	v_readlane_b32 s75, v254, 14
	v_readlane_b32 s76, v254, 15
	v_readlane_b32 s77, v254, 16
	v_readlane_b32 s78, v254, 17
	v_readlane_b32 s79, v254, 18
	v_readlane_b32 s80, v254, 19
	v_readlane_b32 s81, v254, 20
	s_cbranch_vccnz .LBB0_236
	v_mbcnt_lo_u32_b32 v0, -1, 0
	v_mov_b32_e32 v30, 0x42800000
	v_mov_b32_e32 v31, 0x358637bd
	v_mbcnt_hi_u32_b32 v32, -1, v0
	s_mov_b32 s18, s92
	s_branch .LBB0_230

; #define LAS __attribute__((address_space(3)))
; DI float bf2f(unsigned short u) { return __uint_as_float(((unsigned)u) << 16); }
; DI void attn_decode_unit(LAS unsigned char* lds, const bf16_t* Z, const float* ck, const float* cv, bf16_t* MIX, const float* gq, const float* gk, const float* sinks, float* o_k, float* o_v, int b, int kh, int tid) {
;     LAS float* Kc = (LAS float*)lds; LAS float* Vc = Kc + 129 * 68; LAS float* qs = Vc + 129 * 64; LAS float* pw = qs + 512;
;     const int lane = tid & 63, wid = tid >> 6;
; #pragma unroll
;     for (int k = 0; k < 4; ++k) {
;         const int it = k * 512 + tid, w = it >> 4, c4 = (it & 15) * 4;
;         const size_t src = ((size_t)(b * 128 + w) * 2 + kh) * 64 + c4;
;         const f32x4 k4 = *(const f32x4*)(ck + src), v4 = *(const f32x4*)(cv + src);
;         *(LAS f32x4*)(Kc + w * 68 + c4) = k4; *(LAS f32x4*)(Vc + w * 64 + c4) = v4;
;         if (w >= 1) { const size_t dst = ((size_t)(b * 128 + w - 1) * 2 + kh) * 64 + c4; *(f32x4*)(o_k + dst) = k4; *(f32x4*)(o_v + dst) = v4; }
;     }
;     const bf16_t* zrow = Z + (size_t)(LP + b) * INW;
;     const size_t dnew = ((size_t)(b * 128 + 127) * 2 + kh) * 64 + lane;
;     if (wid == 0) { const float kx = bf2f(zrow[C_AK + kh * 64 + lane]); const float ss = wave_sum(kx * kx); const float kn = kx * rsqrtf(ss * (1.0f / 64.0f) + EPS) * gk[lane];
;         Kc[128 * 68 + lane] = kn; o_k[dnew] = kn; }
;     if (wid == 1) { const float vx = bf2f(zrow[C_AV + kh * 64 + lane]); Vc[128 * 64 + lane] = vx; o_v[dnew] = vx; }
;     const int hq = kh * 8 + wid;
;     { const float qx = bf2f(zrow[hq * 64 + lane]); const float ss = wave_sum(qx * qx); qs[wid * 64 + lane] = qx * rsqrtf(ss * (1.0f / 64.0f) + EPS) * gq[lane] * 0.125f; }
; __global__ void __launch_bounds__(512, 2) fwd_kernel(Args a) {
;     ...
;         if (bx & 1) for (int u = bx; u < 256; u += G) attn_decode_unit(lds, Z, cache_k, cache_v, MIX, gq, gk, sinks, out + O_KS, out + O_VS, u >> 1, u & 1, tid);
;         for (int u = 256 + bx; u < 512; u += G) ret_decode_unit(lds, Z, state0, out + O_SS, MIX, rng, u >> 2, u & 3, tid);
;         if (!(bx & 1)) for (int u = bx; u < 256; u += G) attn_decode_unit(lds, Z, cache_k, cache_v, MIX, gq, gk, sinks, out + O_KS, out + O_VS, u >> 1, u & 1, tid);
.LBB0_310:
	v_readlane_b32 s0, v254, 39
	v_readlane_b32 s1, v254, 40
	s_or_b64 exec, exec, s[0:1]
	v_readlane_b32 s92, v254, 37
	s_bitcmp0_b32 s92, 4
	v_readlane_b32 s68, v254, 7
	s_cselect_b64 s[18:19], -1, 0
	s_cmpk_gt_i32 s92, 0xff
	v_readlane_b32 s82, v254, 21
	s_cselect_b64 s[4:5], -1, 0
	v_readlane_b32 s83, v254, 22
	s_add_u32 s14, s82, 0x4220000
	s_addc_u32 s15, s83, 0
	s_add_u32 s16, s82, 0x4a20000
	v_add_u32_e32 v3, 0x200, v253
	s_addc_u32 s17, s83, 0
	v_lshlrev_b32_e32 v0, 2, v253
	v_lshrrev_b32_e32 v42, 4, v3
	v_add_u32_e32 v3, 0x600, v253
	v_lshlrev_b32_e32 v8, 2, v152
	s_add_i32 s6, 0, 0x10a10
	v_lshrrev_b32_e32 v44, 4, v3
	v_add_u32_e32 v3, 0, v8
	v_add_u32_e32 v47, s6, v0
	s_movk_i32 s6, 0x10c
	s_add_i32 s7, 0, 0x11210
	v_and_b32_e32 v40, 60, v0
	v_lshrrev_b32_e32 v41, 4, v253
	v_mad_u32_u24 v48, v152, s6, v3
	s_movk_i32 s6, 0x210
	v_mov_b32_e32 v4, s7
	v_readlane_b32 s69, v254, 8
	v_mov_b32_e32 v9, 0
	v_lshl_add_u32 v56, v40, 2, 0
	v_mul_u32_u24_e32 v1, 0x110, v41
	v_lshlrev_b32_e32 v2, 8, v41
	v_or_b32_e32 v43, 64, v41
	v_add_u32_e32 v46, 0x8910, v3
	v_mul_u32_u24_e32 v3, 0x210, v252
	v_mad_u32_u24 v50, v252, s6, v4
	s_or_b64 s[4:5], s[18:19], s[4:5]
	v_readlane_b32 s84, v254, 27
	v_readlane_b32 s86, v254, 29
	v_readlane_b32 s88, v254, 31
	v_readlane_b32 s90, v254, 35
	s_mov_b32 s21, 0
	v_mul_u32_u24_e32 v57, 0x110, v42
	v_lshlrev_b32_e32 v58, 8, v42
	v_lshlrev_b32_e32 v59, 8, v43
	v_mul_u32_u24_e32 v60, 0x110, v44
	v_lshlrev_b32_e32 v61, 8, v44
	v_cmp_gt_u32_e64 s[0:1], 64, v253
	v_lshl_add_u64 v[20:21], s[68:69], 0, v[8:9]
	v_add_u32_e32 v45, 0, v0
	v_cmp_eq_u32_e64 s[8:9], 1, v252
	v_lshl_add_u64 v[22:23], s[58:59], 0, v[8:9]
	v_mul_i32_i24_e32 v49, 0xfffffef4, v152
	v_add_u32_e32 v51, v50, v8
	v_cmp_eq_u32_e64 s[10:11], 0, v152
	v_and_b32_e32 v62, 0xfc, v0
	s_and_b64 vcc, exec, s[4:5]
	v_lshl_add_u32 v52, v252, 8, 0
	v_add_u32_e32 v53, 0, v3
	v_lshlrev_b32_e32 v24, 1, v152
	v_add_u32_e32 v54, v56, v1
	v_add_u32_e32 v55, v56, v2
	v_readlane_b32 s85, v254, 28
	v_readlane_b32 s87, v254, 30
	v_readlane_b32 s89, v254, 32
	v_readlane_b32 s91, v254, 36
	v_readlane_b32 s93, v254, 38
	v_readlane_b32 s70, v254, 9
	v_readlane_b32 s71, v254, 10
	v_readlane_b32 s72, v254, 11
	v_readlane_b32 s73, v254, 12
	v_readlane_b32 s74, v254, 13
	v_readlane_b32 s75, v254, 14
	v_readlane_b32 s76, v254, 15
	v_readlane_b32 s77, v254, 16
	v_readlane_b32 s78, v254, 17
	v_readlane_b32 s79, v254, 18
	v_readlane_b32 s80, v254, 19
	v_readlane_b32 s81, v254, 20
	s_cbranch_vccnz .LBB0_325
	v_mbcnt_lo_u32_b32 v0, -1, 0
	v_mbcnt_hi_u32_b32 v0, -1, v0
	v_and_b32_e32 v1, 64, v0
	v_add_u32_e32 v1, 64, v1
	v_xor_b32_e32 v2, 1, v0
	v_cmp_lt_i32_e32 vcc, v2, v1
	s_movk_i32 s22, 0xfe00
	s_mov_b32 s23, -1
	v_cndmask_b32_e32 v2, v0, v2, vcc
	v_lshlrev_b32_e32 v14, 2, v2
	v_xor_b32_e32 v2, 2, v0
	v_cmp_lt_i32_e32 vcc, v2, v1
	v_mov_b32_e32 v27, 0x358637bd
	s_mov_b32 s12, 0x800000
	v_cndmask_b32_e32 v2, v0, v2, vcc
	v_lshlrev_b32_e32 v15, 2, v2
	v_xor_b32_e32 v2, 4, v0
	v_cmp_lt_i32_e32 vcc, v2, v1
	s_mov_b32 s13, s92
	s_nop 0
	v_cndmask_b32_e32 v2, v0, v2, vcc
	v_lshlrev_b32_e32 v16, 2, v2
	v_xor_b32_e32 v2, 8, v0
	v_cmp_lt_i32_e32 vcc, v2, v1
	s_nop 1
	v_cndmask_b32_e32 v2, v0, v2, vcc
	v_lshlrev_b32_e32 v17, 2, v2
	v_xor_b32_e32 v2, 16, v0
	v_cmp_lt_i32_e32 vcc, v2, v1
	s_nop 1
	v_cndmask_b32_e32 v2, v0, v2, vcc
	v_lshlrev_b32_e32 v18, 2, v2
	v_xor_b32_e32 v2, 32, v0
	v_cmp_lt_i32_e32 vcc, v2, v1
	s_nop 1
	v_cndmask_b32_e32 v0, v0, v2, vcc
	v_lshlrev_b32_e32 v19, 2, v0
	v_add_u32_e32 v0, 0, v62
	v_add_u32_e32 v26, 0x8910, v0
